# P0 rmsnorm1 loop: the four norm1_w vectors loaded with the row loads; no per-quarter vmcnt(0) drain of the H1 stores
# speedup vs baseline: 1.0059x; 1.0059x over previous
.LBB0_25:
	s_add_i32 s2, s0, s12
	s_cmpk_lt_i32 s2, 0x4100
	s_cselect_b64 s[10:11], -1, 0
	s_and_b64 s[4:5], s[10:11], exec
	s_cselect_b32 s3, s2, s0
	s_add_i32 s4, s0, 0xffffc000
	s_ashr_i32 s1, s0, 31
	s_cmpk_lt_i32 s0, 0x4000
	s_cselect_b32 s5, s1, 0
	s_cselect_b32 s4, s0, s4
	s_cselect_b32 s13, s77, s79
	s_cselect_b32 s14, s76, s78
	s_lshl_b64 s[4:5], s[4:5], 12
	s_add_u32 s4, s14, s4
	s_addc_u32 s5, s13, s5
	global_load_dwordx4 v[54:57], v51, s[4:5]
	global_load_dwordx4 v[22:25], v51, s[4:5] offset:1024
	global_load_dwordx4 v[6:9], v51, s[4:5] offset:3072
	global_load_dwordx4 v[14:17], v51, s[4:5] offset:2048
	s_add_i32 s4, s3, 0xffffc000
	s_ashr_i32 s5, s3, 31
	s_cmpk_lt_i32 s3, 0x4000
	s_cselect_b32 s5, s5, 0
	s_cselect_b32 s4, s3, s4
	s_cselect_b32 s3, s77, s79
	s_cselect_b32 s13, s76, s78
	s_lshl_b64 s[4:5], s[4:5], 12
	s_add_u32 s4, s13, s4
	s_addc_u32 s5, s3, s5
	global_load_dwordx4 v[26:29], v51, s[4:5]
	global_load_dwordx4 v[18:21], v51, s[4:5] offset:1024
	global_load_dwordx4 v[10:13], v51, s[4:5] offset:2048
	global_load_dwordx4 v[2:5], v51, s[4:5] offset:3072
	global_load_dwordx4 v[68:71], v[34:35], off offset:1024
	global_load_dwordx4 v[72:75], v[34:35], off offset:2048
	global_load_dwordx4 v[76:79], v[34:35], off offset:3072
	global_load_dwordx4 v[30:33], v[34:35], off
	s_ashr_i32 s3, s2, 31
	s_lshl_b64 s[0:1], s[0:1], 11
	s_lshl_b64 s[4:5], s[2:3], 11
	s_cmpk_gt_i32 s2, 0x40ff
	s_waitcnt vmcnt(11)
	v_pk_mul_f32 v[38:39], v[56:57], v[56:57]
	v_pk_mul_f32 v[40:41], v[54:55], v[54:55]
	s_waitcnt vmcnt(10)
	v_pk_mul_f32 v[44:45], v[24:25], v[24:25]
	v_pk_mul_f32 v[58:59], v[22:23], v[22:23]
	v_pk_mov_b32 v[62:63], v[40:41], v[38:39] op_sel:[1,0]
	v_mov_b32_e32 v41, v39
	v_pk_mov_b32 v[38:39], v[58:59], v[44:45] op_sel:[1,0]
	v_mov_b32_e32 v59, v45
	s_waitcnt vmcnt(8)
	v_mul_f32_e32 v42, v15, v15
	v_mul_f32_e32 v60, v17, v17
	v_pk_add_f32 v[40:41], v[62:63], v[40:41]
	v_pk_add_f32 v[38:39], v[38:39], v[58:59]
	v_mul_f32_e32 v53, v6, v6
	v_mul_f32_e32 v64, v7, v7
	v_mul_f32_e32 v65, v8, v8
	v_mul_f32_e32 v66, v9, v9
	v_pk_fma_f32 v[44:45], v[14:15], v[14:15], v[42:43] op_sel_hi:[1,1,0]
	v_pk_fma_f32 v[60:61], v[16:17], v[16:17], v[60:61] op_sel_hi:[1,1,0]
	v_pk_add_f32 v[40:41], v[40:41], v[40:41] op_sel:[0,1] op_sel_hi:[1,0]
	v_pk_add_f32 v[38:39], v[38:39], v[38:39] op_sel:[0,1] op_sel_hi:[1,0]
	v_mov_b32_e32 v45, v65
	v_mov_b32_e32 v61, v66
	v_mov_b32_e32 v41, v53
	v_mov_b32_e32 v39, v64
	v_pk_add_f32 v[44:45], v[44:45], v[60:61]
	s_waitcnt vmcnt(7)
	v_mul_f32_e32 v42, v27, v27
	v_mul_f32_e32 v53, v29, v29
	s_waitcnt vmcnt(6)
	v_mul_f32_e32 v58, v19, v19
	v_mul_f32_e32 v59, v21, v21
	v_pk_add_f32 v[38:39], v[40:41], v[38:39]
	s_waitcnt vmcnt(5)
	v_mul_f32_e32 v60, v11, v11
	v_mul_f32_e32 v61, v13, v13
	s_waitcnt vmcnt(4)
	v_mul_f32_e32 v40, v3, v3
	v_mul_f32_e32 v41, v5, v5
	v_fmac_f32_e32 v42, v26, v26
	v_fmac_f32_e32 v53, v28, v28
	v_fmac_f32_e32 v58, v18, v18
	v_fmac_f32_e32 v59, v20, v20
	v_pk_add_f32 v[38:39], v[38:39], v[44:45]
	v_fmac_f32_e32 v60, v10, v10
	v_fmac_f32_e32 v61, v12, v12
	v_fmac_f32_e32 v40, v2, v2
	v_fmac_f32_e32 v41, v4, v4
	v_add_f32_e32 v42, v42, v53
	v_add_f32_e32 v44, v58, v59
	v_add_f32_e32 v38, v38, v39
	v_add_f32_e32 v45, v60, v61
	v_add_f32_e32 v39, v40, v41
	v_add_f32_e32 v40, v42, v44
	ds_bpermute_b32 v41, v43, v38
	v_add_f32_e32 v40, v40, v45
	v_add_f32_e32 v39, v40, v39
	ds_bpermute_b32 v40, v43, v39
	s_waitcnt lgkmcnt(1)
	v_add_f32_e32 v38, v38, v41
	ds_bpermute_b32 v41, v46, v38
	s_waitcnt lgkmcnt(1)
	v_add_f32_e32 v39, v39, v40
	ds_bpermute_b32 v40, v46, v39
	s_waitcnt lgkmcnt(1)
	v_add_f32_e32 v38, v38, v41
	ds_bpermute_b32 v41, v47, v38
	s_waitcnt lgkmcnt(1)
	v_add_f32_e32 v39, v39, v40
	ds_bpermute_b32 v40, v47, v39
	s_waitcnt lgkmcnt(1)
	v_add_f32_e32 v38, v38, v41
	ds_bpermute_b32 v41, v48, v38
	s_waitcnt lgkmcnt(1)
	v_add_f32_e32 v39, v39, v40
	ds_bpermute_b32 v40, v48, v39
	s_waitcnt lgkmcnt(1)
	v_add_f32_e32 v38, v38, v41
	ds_bpermute_b32 v42, v49, v38
	s_waitcnt lgkmcnt(1)
	v_add_f32_e32 v39, v39, v40
	ds_bpermute_b32 v44, v49, v39
	v_lshl_add_u64 v[40:41], v[36:37], 0, s[0:1]
	s_waitcnt lgkmcnt(1)
	v_add_f32_e32 v42, v38, v42
	ds_bpermute_b32 v45, v50, v42
	s_waitcnt lgkmcnt(1)
	v_add_f32_e32 v53, v39, v44
	ds_bpermute_b32 v58, v50, v53
	v_lshl_add_u64 v[38:39], v[36:37], 0, s[4:5]
	s_waitcnt lgkmcnt(1)
	v_add_f32_e32 v42, v42, v45
	v_fmamk_f32 v42, v42, 0x3a800000, v52
	v_rsq_f32_e32 v44, v42
	s_waitcnt lgkmcnt(0)
	v_add_f32_e32 v42, v53, v58
	v_fmamk_f32 v42, v42, 0x3a800000, v52
	v_rsq_f32_e32 v42, v42
	v_pk_mul_f32 v[54:55], v[44:45], v[54:55] op_sel_hi:[0,1]
	v_pk_mul_f32 v[56:57], v[44:45], v[56:57] op_sel_hi:[0,1]
	s_waitcnt vmcnt(0)
	v_pk_mul_f32 v[54:55], v[54:55], v[30:31]
	v_pk_mul_f32 v[56:57], v[56:57], v[32:33]
	v_cvt_pk_bf16_f32 v54, v54, v55
	v_cvt_pk_bf16_f32 v55, v56, v57
	global_store_dwordx2 v[40:41], v[54:55], off
	s_cbranch_scc1 .LBB0_27
	v_pk_mul_f32 v[26:27], v[42:43], v[26:27] op_sel_hi:[0,1]
	v_pk_mul_f32 v[28:29], v[42:43], v[28:29] op_sel_hi:[0,1]
	v_pk_mul_f32 v[26:27], v[26:27], v[30:31]
	v_pk_mul_f32 v[28:29], v[28:29], v[32:33]
	v_cvt_pk_bf16_f32 v26, v26, v27
	v_cvt_pk_bf16_f32 v27, v28, v29
	global_store_dwordx2 v[38:39], v[26:27], off
.LBB0_27:
	v_mov_b32_e32 v26, v68
	v_mov_b32_e32 v27, v69
	v_mov_b32_e32 v28, v70
	v_mov_b32_e32 v29, v71
	v_mov_b32_e32 v45, v44
	v_pk_mul_f32 v[22:23], v[44:45], v[22:23]
	v_pk_mul_f32 v[24:25], v[44:45], v[24:25]
	v_cndmask_b32_e64 v30, 0, 1, s[10:11]
	v_cmp_ne_u32_e64 s[4:5], 1, v30
	s_andn2_b64 vcc, exec, s[10:11]
	v_pk_mul_f32 v[22:23], v[22:23], v[26:27]
	v_pk_mul_f32 v[24:25], v[24:25], v[28:29]
	v_cvt_pk_bf16_f32 v22, v22, v23
	v_cvt_pk_bf16_f32 v23, v24, v25
	global_store_dwordx2 v[40:41], v[22:23], off offset:512
	s_cbranch_vccnz .LBB0_29
	v_pk_mul_f32 v[18:19], v[42:43], v[18:19] op_sel_hi:[0,1]
	v_pk_mul_f32 v[20:21], v[42:43], v[20:21] op_sel_hi:[0,1]
	v_pk_mul_f32 v[18:19], v[18:19], v[26:27]
	v_pk_mul_f32 v[20:21], v[20:21], v[28:29]
	v_cvt_pk_bf16_f32 v18, v18, v19
	v_cvt_pk_bf16_f32 v19, v20, v21
	global_store_dwordx2 v[38:39], v[18:19], off offset:512
.LBB0_29:
	v_mov_b32_e32 v18, v72
	v_mov_b32_e32 v19, v73
	v_mov_b32_e32 v20, v74
	v_mov_b32_e32 v21, v75
	v_pk_mul_f32 v[14:15], v[44:45], v[14:15]
	v_pk_mul_f32 v[16:17], v[44:45], v[16:17]
	s_and_b64 vcc, exec, s[4:5]
	v_pk_mul_f32 v[14:15], v[14:15], v[18:19]
	v_pk_mul_f32 v[16:17], v[16:17], v[20:21]
	v_cvt_pk_bf16_f32 v14, v14, v15
	v_cvt_pk_bf16_f32 v15, v16, v17
	global_store_dwordx2 v[40:41], v[14:15], off offset:1024
	s_cbranch_vccnz .LBB0_31
	v_pk_mul_f32 v[10:11], v[42:43], v[10:11] op_sel_hi:[0,1]
	v_pk_mul_f32 v[12:13], v[42:43], v[12:13] op_sel_hi:[0,1]
	v_pk_mul_f32 v[10:11], v[10:11], v[18:19]
	v_pk_mul_f32 v[12:13], v[12:13], v[20:21]
	v_cvt_pk_bf16_f32 v10, v10, v11
	v_cvt_pk_bf16_f32 v11, v12, v13
	global_store_dwordx2 v[38:39], v[10:11], off offset:1024
.LBB0_31:
	v_mov_b32_e32 v10, v76
	v_mov_b32_e32 v11, v77
	v_mov_b32_e32 v12, v78
	v_mov_b32_e32 v13, v79
	v_pk_mul_f32 v[6:7], v[44:45], v[6:7]
	v_pk_mul_f32 v[8:9], v[44:45], v[8:9]
	s_and_b64 vcc, exec, s[4:5]
	v_pk_mul_f32 v[6:7], v[6:7], v[10:11]
	v_pk_mul_f32 v[8:9], v[8:9], v[12:13]
	v_cvt_pk_bf16_f32 v6, v6, v7
	v_cvt_pk_bf16_f32 v7, v8, v9
	global_store_dwordx2 v[40:41], v[6:7], off offset:1536
	s_cbranch_vccnz .LBB0_24
	v_pk_mul_f32 v[2:3], v[42:43], v[2:3] op_sel_hi:[0,1]
	v_pk_mul_f32 v[4:5], v[42:43], v[4:5] op_sel_hi:[0,1]
	v_pk_mul_f32 v[2:3], v[2:3], v[10:11]
	v_pk_mul_f32 v[4:5], v[4:5], v[12:13]
	v_cvt_pk_bf16_f32 v2, v2, v3
	v_cvt_pk_bf16_f32 v3, v4, v5
	global_store_dwordx2 v[38:39], v[2:3], off offset:1536
	s_branch .LBB0_24
